# P1 epilogue: stores bounced through LDS so 4 lanes write 64 contiguous bytes, hand-written path for activation-free sections, 4-group 1.3us start stagger
# speedup vs baseline: 1.0105x; 1.0070x over previous
;     __host__ __device__ void init(int M, int N, int G_, int c_) { base.init(M, N, G_, c_); }
; __global__ void __launch_bounds__(512) mk_fwd(Args a) {
;     ...
;     if (PH_MASK & 2) {
;         pg8::Gemm g{(const bf16_t*)a.out, (const bf16_t*)(ws + WS_WIN), M_TOK, NPROJ, 1024}; pg8::StaticOrder S; S.init(M_TOK, NPROJ, G, blk);
;         pg8::EpiProj E{ws};
;         for (int rep = 0; rep < REP_P1; ++rep)
;         pg8::gemm_phase<pg8::EpiProj, pg8::StaticOrder, true, true>(lds, g, S, E);
.LBB0_113:
	s_bfe_u32 s98, s2, 0x20003
	s_cmp_eq_u32 s98, 0
	s_cbranch_scc1 .Lstg1_done
.Lstg1_loop:
	s_sleep 35
	s_sub_u32 s98, s98, 1
	s_cmp_lg_u32 s98, 0
	s_cbranch_scc1 .Lstg1_loop

;     __device__ __forceinline__ void operator()(const f32x4 (&acc)[2][2][4][2], const Unit& u, int wr, int wc, int fr, int fq) const {
;         const int pn = u.pn; const int row0 = u.pm * BM + wr * 64 + fr;
;         size_t off; int ldc = 1024, colt, act = 0;
;         if (pn < 16) { off = WS_QK + (size_t)(pn >> 2) * (64 * MiB); colt = (pn & 3) * 256; if ((pn >> 2) == 2) act = 2; }
;         else if (pn < 18) { off = WS_SKV; ldc = 512; colt = (pn - 16) * 256; }
;         else if (pn < 22) { off = WS_GA; colt = (pn - 18) * 256; act = 1; }
;         else { off = WS_GB; colt = (pn - 22) * 256; act = 1; }
;         bf16_t* base = (bf16_t*)(ws + off);
;         const int col0 = colt + wc * 32 + 8 * fq;
; template <class Epi, class Sched, bool ALIGN_EPI = false, bool SP2 = false>
; __device__ __forceinline__ void gemm_phase(PG8_LAS unsigned char* lds, const Gemm g, const Sched& S, const Epi& E) {
;     int tid_ = threadIdx.x; asm volatile("" : "+v"(tid_));
;     const int tid = tid_, wid = __builtin_amdgcn_readfirstlane(tid >> 6), lane = tid & 63, wr = wid >> 2, wc = wid & 3, fr = lane & 15, fq = lane >> 4;
;     const int K = g.K, nt = K / BK;
;     unsigned voffA[2], voffB[2];
; #pragma unroll
;     for (int i = 0; i < 2; ++i) { int R, C; stage_rc(tid * 16 + i * 8192, R, C); const int Rb = Epi::PERM ? ((R & ~31) + perm32(R & 31)) : R;
;         voffA[i] = (unsigned)(R * K + C) * 2u; voffB[i] = (unsigned)(Rb * K + C) * 2u; }
;     const size_t kstep = (size_t)(BK * 2);
;     const size_t hstep = (size_t)HALF * K * 2;
;     const size_t tstep = 2 * hstep;
;     const unsigned ldsw = (unsigned)wid * 1024u;
;     const int aoff = lds_byte(wr * 64 + fr, fq * 8), boff = lds_byte(wc * 32 + fr, fq * 8);
.LBB0_118:
	s_lshl_b32 s1, s1, 5
	s_mov_b64 s[18:19], 0x80
	s_and_b32 s1, s1, 0x60
	s_add_i32 m0, s87, 0x18000
	v_lshl_add_u64 v[6:7], v[6:7], 0, s[18:19]
	s_lshl_b32 s5, s0, 13
	s_lshl_b32 s7, s1, 7
	s_waitcnt vmcnt(2)
	s_barrier
	global_load_lds_dwordx4 v[6:7], off
	v_lshl_add_u64 v[4:5], v[4:5], 0, s[18:19]
	s_add_i32 m0, s87, 0x1a000
	s_add_i32 s92, s87, 0x8000
	s_add_i32 s93, s87, 0xa000
	global_load_lds_dwordx4 v[4:5], off
	v_lshl_add_u64 v[0:1], v[0:1], 0, s[18:19]
	s_mov_b32 m0, s92
	s_add_u32 s8, s80, 0x40080
	global_load_lds_dwordx4 v[0:1], off
	v_lshl_add_u64 v[0:1], v[2:3], 0, s[18:19]
	s_mov_b32 m0, s93
	s_addc_u32 s9, s81, 0
	global_load_lds_dwordx4 v[0:1], off
	s_add_i32 m0, s87, 0x1c000
	v_lshl_add_u64 v[0:1], s[8:9], 0, v[130:131]
	global_load_lds_dwordx4 v[0:1], off
	v_lshl_add_u64 v[0:1], s[8:9], 0, v[134:135]
	s_add_i32 m0, s87, 0x1e000
	s_cmpk_lt_u32 s3, 0x100
	global_load_lds_dwordx4 v[0:1], off
	v_lshrrev_b32_e32 v1, 1, v8
	v_and_b32_e32 v1, 24, v1
	v_and_b32_e32 v0, 15, v8
	v_lshlrev_b32_e32 v2, 1, v1
	v_bfe_u32 v154, v8, 2, 4
	v_lshl_or_b32 v154, s0, 6, v154
	v_lshl_or_b32 v0, v0, 6, v2
	v_lshlrev_b32_e32 v2, 2, v8
	v_and_b32_e32 v2, 32, v2
	v_bitop3_b32 v3, v0, s5, v2 bitop3:0xde
	v_bitop3_b32 v155, v0, s7, v2 bitop3:0xde
	v_lshlrev_b32_e32 v0, 14, v9
	v_and_b32_e32 v0, 0xffff8000, v0
	v_and_b32_e32 v156, 3, v8
	v_lshlrev_b32_e32 v156, 3, v156
	v_or_b32_e32 v156, s1, v156
	v_lshrrev_b32_e32 v230, 6, v8
	v_mul_u32_u24_e32 v230, 0x500, v230
	v_add_u32_e32 v230, 0x20000, v230
	v_and_b32_e32 v228, 15, v8
	v_mul_u32_u24_e32 v228, 0x50, v228
	v_bfe_u32 v231, v8, 4, 2
	v_lshl_add_u32 v228, v231, 4, v228
	v_add_u32_e32 v228, v228, v230
	v_bfe_u32 v229, v8, 2, 4
	v_mul_u32_u24_e32 v229, 0x50, v229
	v_and_b32_e32 v231, 3, v8
	v_lshl_add_u32 v229, v231, 4, v229
	v_add_u32_e32 v229, v229, v230
	v_lshl_add_u32 v0, v10, 11, v0
	v_and_b32_e32 v1, 1, v9
	v_lshl_or_b32 v0, v1, 6, v0
	v_lshl_add_u32 v138, v11, 1, v0
	v_lshlrev_b32_e32 v0, 14, v12
	v_and_b32_e32 v0, 0xffff8000, v0
	s_waitcnt vmcnt(6)
	v_lshl_add_u32 v0, v13, 11, v0
	v_and_b32_e32 v1, 1, v12
	s_cselect_b64 s[20:21], -1, 0
	v_lshl_or_b32 v0, v1, 6, v0
	s_add_i32 s94, 0, 0x10000
	s_add_i32 s95, 0, 0x14000
	v_mov_b32_e32 v139, v137
	v_lshl_add_u32 v140, v14, 1, v0
	v_mov_b32_e32 v141, v137
	v_mov_b64_e32 v[142:143], 0xd00
	v_mov_b64_e32 v[144:145], 0xcff
	v_add_u32_e32 v157, s94, v155
	v_add_u32_e32 v158, s95, v155
	v_add_u32_e32 v159, 0, v3
	s_barrier
	s_branch .LBB0_121

; __device__ __forceinline__ float sigm(float x) { return __builtin_amdgcn_rcpf(1.f + __builtin_amdgcn_exp2f(-1.4426950408889634f * x)); }
;     __device__ __forceinline__ void operator()(const f32x4 (&acc)[2][2][4][2], const Unit& u, int wr, int wc, int fr, int fq) const {
;     ...
;         if (pn < 16) { off = WS_QK + (size_t)(pn >> 2) * (64 * MiB); colt = (pn & 3) * 256; if ((pn >> 2) == 2) act = 2; }
;         else if (pn < 18) { off = WS_SKV; ldc = 512; colt = (pn - 16) * 256; }
;         else if (pn < 22) { off = WS_GA; colt = (pn - 18) * 256; act = 1; }
;         else { off = WS_GB; colt = (pn - 22) * 256; act = 1; }
;         bf16_t* base = (bf16_t*)(ws + off);
;         const int col0 = colt + wc * 32 + 8 * fq;
; #pragma unroll
;         for (int ai = 0; ai < 2; ++ai)
; #pragma unroll
;             for (int m = 0; m < 4; ++m) { bf16_t* rowp = base + (size_t)(row0 + ai * HALF + m * 16) * ldc + col0;
; #pragma unroll
;                 for (int bj = 0; bj < 2; ++bj) { const f32x4 v0 = acc[ai][bj][m][0], v1 = acc[ai][bj][m][1];
;                     float f[8] = {v0[0], v0[1], v0[2], v0[3], v1[0], v1[1], v1[2], v1[3]};
;                     if (act == 1) {
; #pragma unroll
;                         for (int e = 0; e < 8; ++e) f[e] = sigm(f[e]);
;                     } else if (act == 2) {
; #pragma unroll
;                         for (int e = 0; e < 8; ++e) f[e] = f[e] * sigm(f[e]);
;                     }
.LBB0_139:
	s_or_b64 s[98:99], s[82:83], s[84:85]
	s_cmp_eq_u64 s[98:99], 0
	s_cbranch_scc1 .Lp1_plain
	s_xor_b64 s[82:83], s[82:83], -1
	v_cndmask_b32_e64 v136, 0, 1, s[84:85]
	s_mov_b64 s[8:9], -1
	s_and_b64 vcc, exec, s[82:83]
	v_cmp_ne_u32_e64 s[4:5], 1, v136
	s_cbranch_vccz .LBB0_142
	s_and_b64 vcc, exec, s[4:5]
	s_cbranch_vccnz .LBB0_222
	v_mul_f32_e32 v136, 0xbfb8aa3b, v124
	v_exp_f32_e32 v136, v136
	v_mul_f32_e32 v146, 0xbfb8aa3b, v125
	v_mul_f32_e32 v147, 0xbfb8aa3b, v126
	v_exp_f32_e32 v148, v146
	v_exp_f32_e32 v149, v147
	v_add_f32_e32 v136, 1.0, v136
	v_rcp_f32_e32 v146, v136
	v_add_f32_e32 v136, 1.0, v148
	v_mul_f32_e32 v148, 0xbfb8aa3b, v127
	v_rcp_f32_e32 v147, v136
	v_add_f32_e32 v136, 1.0, v149
	v_exp_f32_e32 v149, v148
	v_mul_f32_e32 v148, 0xbfb8aa3b, v120
	v_exp_f32_e32 v150, v148
	v_rcp_f32_e32 v148, v136
	v_add_f32_e32 v136, 1.0, v149
	v_rcp_f32_e32 v149, v136
	v_add_f32_e32 v136, 1.0, v150
	v_mul_f32_e32 v151, 0xbfb8aa3b, v122
	v_rcp_f32_e32 v150, v136
	v_mul_f32_e32 v136, 0xbfb8aa3b, v121
	v_exp_f32_e32 v151, v151
	v_mul_f32_e32 v152, 0xbfb8aa3b, v123
	v_exp_f32_e32 v136, v136
	v_exp_f32_e32 v153, v152
	v_add_f32_e32 v151, 1.0, v151
	v_rcp_f32_e32 v152, v151
	v_add_f32_e32 v136, 1.0, v136
	v_add_f32_e32 v151, 1.0, v153
	v_rcp_f32_e32 v153, v151
	v_rcp_f32_e32 v151, v136
	v_pk_mul_f32 v[148:149], v[126:127], v[148:149]
	v_pk_mul_f32 v[146:147], v[124:125], v[146:147]
	v_pk_mul_f32 v[152:153], v[122:123], v[152:153]
	v_pk_mul_f32 v[150:151], v[120:121], v[150:151]
	s_mov_b64 s[8:9], 0

; __device__ __forceinline__ u32x4 pack8(const float (&f)[8]) { u32x4 w; w.x = cvt_pk_bf16(f[0], f[1]); w.y = cvt_pk_bf16(f[2], f[3]); w.z = cvt_pk_bf16(f[4], f[5]); w.w = cvt_pk_bf16(f[6], f[7]); return w; }
; __device__ __forceinline__ float sigm(float x) { return __builtin_amdgcn_rcpf(1.f + __builtin_amdgcn_exp2f(-1.4426950408889634f * x)); }
;     __device__ __forceinline__ void operator()(const f32x4 (&acc)[2][2][4][2], const Unit& u, int wr, int wc, int fr, int fq) const {
;     ...
;         for (int ai = 0; ai < 2; ++ai)
; #pragma unroll
;             for (int m = 0; m < 4; ++m) { bf16_t* rowp = base + (size_t)(row0 + ai * HALF + m * 16) * ldc + col0;
; #pragma unroll
;                 for (int bj = 0; bj < 2; ++bj) { const f32x4 v0 = acc[ai][bj][m][0], v1 = acc[ai][bj][m][1];
;                     float f[8] = {v0[0], v0[1], v0[2], v0[3], v1[0], v1[1], v1[2], v1[3]};
;                     if (act == 1) {
; #pragma unroll
;                         for (int e = 0; e < 8; ++e) f[e] = sigm(f[e]);
;                     } else if (act == 2) {
; #pragma unroll
;                         for (int e = 0; e < 8; ++e) f[e] = f[e] * sigm(f[e]);
;                     }
;                     __builtin_nontemporal_store(pack8(f), (u32x4*)(rowp + bj * HALF)); } }
.LBB0_144:
	v_lshl_add_u32 v160, s6, 8, v154
	s_add_u32 s6, s68, s80
	s_addc_u32 s7, s69, s81
	v_add_u32_e32 v136, s3, v156
	v_ashrrev_i32_e32 v122, 31, v160
	v_lshl_add_u64 v[120:121], v[136:137], 1, s[6:7]
	v_mul_lo_u32 v136, s78, v122
	v_mul_lo_u32 v124, s79, v160
	v_mad_u64_u32 v[122:123], s[6:7], s78, v160, 0
	v_add3_u32 v123, v123, v136, v124
	v_lshl_add_u64 v[122:123], v[122:123], 1, v[120:121]
	v_cvt_pk_bf16_f32 v124, v146, v147
	v_cvt_pk_bf16_f32 v125, v148, v149
	v_cvt_pk_bf16_f32 v126, v150, v151
	v_cvt_pk_bf16_f32 v127, v152, v153
	ds_write_b128 v228, v[124:127]
	ds_read_b128 v[232:235], v229
	s_waitcnt lgkmcnt(0)
	global_store_dwordx4 v[122:123], v[232:235], off nt
	s_andn2_b64 vcc, exec, s[82:83]
	s_mov_b64 s[8:9], -1
	v_cndmask_b32_e64 v124, 0, 1, s[82:83]
	v_cmp_ne_u32_e64 s[6:7], 1, v124
	s_cbranch_vccnz .LBB0_147
	s_and_b64 vcc, exec, s[4:5]
	s_cbranch_vccnz .LBB0_223
	v_mul_f32_e32 v124, 0xbfb8aa3b, v116
	v_mul_f32_e32 v125, 0xbfb8aa3b, v117
	v_mul_f32_e32 v126, 0xbfb8aa3b, v118
	v_mul_f32_e32 v127, 0xbfb8aa3b, v119
	v_mul_f32_e32 v146, 0xbfb8aa3b, v112
	v_mul_f32_e32 v147, 0xbfb8aa3b, v113
	v_mul_f32_e32 v148, 0xbfb8aa3b, v114
	v_mul_f32_e32 v149, 0xbfb8aa3b, v115
	v_exp_f32_e32 v124, v124
	v_exp_f32_e32 v125, v125
	v_exp_f32_e32 v126, v126
	v_exp_f32_e32 v127, v127
	v_exp_f32_e32 v146, v146
	v_exp_f32_e32 v147, v147
	v_exp_f32_e32 v148, v148
	v_exp_f32_e32 v149, v149
	v_add_f32_e32 v124, 1.0, v124
	v_add_f32_e32 v125, 1.0, v125
	v_add_f32_e32 v126, 1.0, v126
	v_add_f32_e32 v127, 1.0, v127
	v_add_f32_e32 v146, 1.0, v146
	v_add_f32_e32 v147, 1.0, v147
	v_add_f32_e32 v148, 1.0, v148
	v_add_f32_e32 v149, 1.0, v149
	v_rcp_f32_e32 v124, v124
	v_rcp_f32_e32 v125, v125
	v_rcp_f32_e32 v126, v126
	v_rcp_f32_e32 v127, v127
	v_rcp_f32_e32 v146, v146
	v_rcp_f32_e32 v148, v148
	v_rcp_f32_e32 v149, v149
	v_rcp_f32_e32 v147, v147
	v_pk_mul_f32 v[126:127], v[118:119], v[126:127]
	v_pk_mul_f32 v[124:125], v[116:117], v[124:125]
	v_pk_mul_f32 v[148:149], v[114:115], v[148:149]
	v_pk_mul_f32 v[146:147], v[112:113], v[146:147]
	s_mov_b64 s[8:9], 0

; __device__ __forceinline__ u32x4 pack8(const float (&f)[8]) { u32x4 w; w.x = cvt_pk_bf16(f[0], f[1]); w.y = cvt_pk_bf16(f[2], f[3]); w.z = cvt_pk_bf16(f[4], f[5]); w.w = cvt_pk_bf16(f[6], f[7]); return w; }
; __device__ __forceinline__ float sigm(float x) { return __builtin_amdgcn_rcpf(1.f + __builtin_amdgcn_exp2f(-1.4426950408889634f * x)); }
;     __device__ __forceinline__ void operator()(const f32x4 (&acc)[2][2][4][2], const Unit& u, int wr, int wc, int fr, int fq) const {
;     ...
;         for (int ai = 0; ai < 2; ++ai)
; #pragma unroll
;             for (int m = 0; m < 4; ++m) { bf16_t* rowp = base + (size_t)(row0 + ai * HALF + m * 16) * ldc + col0;
; #pragma unroll
;                 for (int bj = 0; bj < 2; ++bj) { const f32x4 v0 = acc[ai][bj][m][0], v1 = acc[ai][bj][m][1];
;                     float f[8] = {v0[0], v0[1], v0[2], v0[3], v1[0], v1[1], v1[2], v1[3]};
;                     if (act == 1) {
; #pragma unroll
;                         for (int e = 0; e < 8; ++e) f[e] = sigm(f[e]);
;                     } else if (act == 2) {
; #pragma unroll
;                         for (int e = 0; e < 8; ++e) f[e] = f[e] * sigm(f[e]);
;                     }
;                     __builtin_nontemporal_store(pack8(f), (u32x4*)(rowp + bj * HALF)); } }
.LBB0_149:
	v_cvt_pk_bf16_f32 v112, v124, v125
	v_cvt_pk_bf16_f32 v113, v126, v127
	v_cvt_pk_bf16_f32 v114, v146, v147
	v_cvt_pk_bf16_f32 v115, v148, v149
	s_and_b64 vcc, exec, s[6:7]
	s_mov_b64 s[8:9], -1
	ds_write_b128 v228, v[112:115]
	ds_read_b128 v[232:235], v229
	s_waitcnt lgkmcnt(0)
	global_store_dwordx4 v[122:123], v[232:235], off offset:256 nt
	s_cbranch_vccnz .LBB0_152
	s_and_b64 vcc, exec, s[4:5]
	s_cbranch_vccnz .LBB0_224
	v_mul_f32_e32 v112, 0xbfb8aa3b, v108
	v_mul_f32_e32 v113, 0xbfb8aa3b, v109
	v_mul_f32_e32 v114, 0xbfb8aa3b, v110
	v_mul_f32_e32 v115, 0xbfb8aa3b, v111
	v_mul_f32_e32 v116, 0xbfb8aa3b, v104
	v_mul_f32_e32 v117, 0xbfb8aa3b, v105
	v_mul_f32_e32 v118, 0xbfb8aa3b, v106
	v_mul_f32_e32 v119, 0xbfb8aa3b, v107
	v_exp_f32_e32 v112, v112
	v_exp_f32_e32 v113, v113
	v_exp_f32_e32 v114, v114
	v_exp_f32_e32 v115, v115
	v_exp_f32_e32 v116, v116
	v_exp_f32_e32 v117, v117
	v_exp_f32_e32 v118, v118
	v_exp_f32_e32 v119, v119
	v_add_f32_e32 v112, 1.0, v112
	v_add_f32_e32 v113, 1.0, v113
	v_add_f32_e32 v114, 1.0, v114
	v_add_f32_e32 v115, 1.0, v115
	v_add_f32_e32 v116, 1.0, v116
	v_add_f32_e32 v117, 1.0, v117
	v_add_f32_e32 v118, 1.0, v118
	v_add_f32_e32 v119, 1.0, v119
	v_rcp_f32_e32 v112, v112
	v_rcp_f32_e32 v113, v113
	v_rcp_f32_e32 v114, v114
	v_rcp_f32_e32 v115, v115
	v_rcp_f32_e32 v116, v116
	v_rcp_f32_e32 v118, v118
	v_rcp_f32_e32 v119, v119
	v_rcp_f32_e32 v117, v117
	v_pk_mul_f32 v[114:115], v[110:111], v[114:115]
	v_pk_mul_f32 v[112:113], v[108:109], v[112:113]
	v_pk_mul_f32 v[118:119], v[106:107], v[118:119]
	v_pk_mul_f32 v[116:117], v[104:105], v[116:117]
	s_mov_b64 s[8:9], 0

; __device__ __forceinline__ u32x4 pack8(const float (&f)[8]) { u32x4 w; w.x = cvt_pk_bf16(f[0], f[1]); w.y = cvt_pk_bf16(f[2], f[3]); w.z = cvt_pk_bf16(f[4], f[5]); w.w = cvt_pk_bf16(f[6], f[7]); return w; }
; __device__ __forceinline__ float sigm(float x) { return __builtin_amdgcn_rcpf(1.f + __builtin_amdgcn_exp2f(-1.4426950408889634f * x)); }
;     __device__ __forceinline__ void operator()(const f32x4 (&acc)[2][2][4][2], const Unit& u, int wr, int wc, int fr, int fq) const {
;     ...
;         for (int ai = 0; ai < 2; ++ai)
; #pragma unroll
;             for (int m = 0; m < 4; ++m) { bf16_t* rowp = base + (size_t)(row0 + ai * HALF + m * 16) * ldc + col0;
; #pragma unroll
;                 for (int bj = 0; bj < 2; ++bj) { const f32x4 v0 = acc[ai][bj][m][0], v1 = acc[ai][bj][m][1];
;                     float f[8] = {v0[0], v0[1], v0[2], v0[3], v1[0], v1[1], v1[2], v1[3]};
;                     if (act == 1) {
; #pragma unroll
;                         for (int e = 0; e < 8; ++e) f[e] = sigm(f[e]);
;                     } else if (act == 2) {
; #pragma unroll
;                         for (int e = 0; e < 8; ++e) f[e] = f[e] * sigm(f[e]);
;                     }
;                     __builtin_nontemporal_store(pack8(f), (u32x4*)(rowp + bj * HALF)); } }
.LBB0_154:
	v_or_b32_e32 v104, 16, v160
	v_mul_lo_u32 v106, s79, v104
	v_mad_u64_u32 v[104:105], s[8:9], s78, v104, 0
	v_add3_u32 v105, v105, v136, v106
	v_lshl_add_u64 v[104:105], v[104:105], 1, v[120:121]
	v_cvt_pk_bf16_f32 v106, v112, v113
	v_cvt_pk_bf16_f32 v107, v114, v115
	v_cvt_pk_bf16_f32 v108, v116, v117
	v_cvt_pk_bf16_f32 v109, v118, v119
	s_and_b64 vcc, exec, s[6:7]
	s_mov_b64 s[8:9], -1
	ds_write_b128 v228, v[106:109]
	ds_read_b128 v[232:235], v229
	s_waitcnt lgkmcnt(0)
	global_store_dwordx4 v[104:105], v[232:235], off nt
	s_cbranch_vccnz .LBB0_157
	s_and_b64 vcc, exec, s[4:5]
	s_cbranch_vccnz .LBB0_225
	v_mul_f32_e32 v106, 0xbfb8aa3b, v100
	v_mul_f32_e32 v107, 0xbfb8aa3b, v101
	v_mul_f32_e32 v108, 0xbfb8aa3b, v102
	v_mul_f32_e32 v109, 0xbfb8aa3b, v103
	v_mul_f32_e32 v110, 0xbfb8aa3b, v96
	v_mul_f32_e32 v111, 0xbfb8aa3b, v97
	v_mul_f32_e32 v112, 0xbfb8aa3b, v98
	v_mul_f32_e32 v113, 0xbfb8aa3b, v99
	v_exp_f32_e32 v106, v106
	v_exp_f32_e32 v107, v107
	v_exp_f32_e32 v108, v108
	v_exp_f32_e32 v109, v109
	v_exp_f32_e32 v110, v110
	v_exp_f32_e32 v111, v111
	v_exp_f32_e32 v112, v112
	v_exp_f32_e32 v113, v113
	v_add_f32_e32 v106, 1.0, v106
	v_add_f32_e32 v107, 1.0, v107
	v_add_f32_e32 v108, 1.0, v108
	v_add_f32_e32 v109, 1.0, v109
	v_add_f32_e32 v110, 1.0, v110
	v_add_f32_e32 v111, 1.0, v111
	v_add_f32_e32 v112, 1.0, v112
	v_add_f32_e32 v113, 1.0, v113
	v_rcp_f32_e32 v106, v106
	v_rcp_f32_e32 v107, v107
	v_rcp_f32_e32 v108, v108
	v_rcp_f32_e32 v109, v109
	v_rcp_f32_e32 v110, v110
	v_rcp_f32_e32 v112, v112
	v_rcp_f32_e32 v113, v113
	v_rcp_f32_e32 v111, v111
	v_pk_mul_f32 v[108:109], v[102:103], v[108:109]
	v_pk_mul_f32 v[106:107], v[100:101], v[106:107]
	v_pk_mul_f32 v[112:113], v[98:99], v[112:113]
	v_pk_mul_f32 v[110:111], v[96:97], v[110:111]
	s_mov_b64 s[8:9], 0

; __device__ __forceinline__ u32x4 pack8(const float (&f)[8]) { u32x4 w; w.x = cvt_pk_bf16(f[0], f[1]); w.y = cvt_pk_bf16(f[2], f[3]); w.z = cvt_pk_bf16(f[4], f[5]); w.w = cvt_pk_bf16(f[6], f[7]); return w; }
; __device__ __forceinline__ float sigm(float x) { return __builtin_amdgcn_rcpf(1.f + __builtin_amdgcn_exp2f(-1.4426950408889634f * x)); }
;     __device__ __forceinline__ void operator()(const f32x4 (&acc)[2][2][4][2], const Unit& u, int wr, int wc, int fr, int fq) const {
;     ...
;         for (int ai = 0; ai < 2; ++ai)
; #pragma unroll
;             for (int m = 0; m < 4; ++m) { bf16_t* rowp = base + (size_t)(row0 + ai * HALF + m * 16) * ldc + col0;
; #pragma unroll
;                 for (int bj = 0; bj < 2; ++bj) { const f32x4 v0 = acc[ai][bj][m][0], v1 = acc[ai][bj][m][1];
;                     float f[8] = {v0[0], v0[1], v0[2], v0[3], v1[0], v1[1], v1[2], v1[3]};
;                     if (act == 1) {
; #pragma unroll
;                         for (int e = 0; e < 8; ++e) f[e] = sigm(f[e]);
;                     } else if (act == 2) {
; #pragma unroll
;                         for (int e = 0; e < 8; ++e) f[e] = f[e] * sigm(f[e]);
;                     }
;                     __builtin_nontemporal_store(pack8(f), (u32x4*)(rowp + bj * HALF)); } }
.LBB0_159:
	v_cvt_pk_bf16_f32 v96, v106, v107
	v_cvt_pk_bf16_f32 v97, v108, v109
	v_cvt_pk_bf16_f32 v98, v110, v111
	v_cvt_pk_bf16_f32 v99, v112, v113
	s_and_b64 vcc, exec, s[6:7]
	s_mov_b64 s[8:9], -1
	ds_write_b128 v228, v[96:99]
	ds_read_b128 v[232:235], v229
	s_waitcnt lgkmcnt(0)
	global_store_dwordx4 v[104:105], v[232:235], off offset:256 nt
	s_cbranch_vccnz .LBB0_162
	s_and_b64 vcc, exec, s[4:5]
	s_cbranch_vccnz .LBB0_226
	v_mul_f32_e32 v96, 0xbfb8aa3b, v92
	v_mul_f32_e32 v97, 0xbfb8aa3b, v93
	v_mul_f32_e32 v98, 0xbfb8aa3b, v94
	v_mul_f32_e32 v99, 0xbfb8aa3b, v95
	v_mul_f32_e32 v100, 0xbfb8aa3b, v88
	v_mul_f32_e32 v101, 0xbfb8aa3b, v89
	v_mul_f32_e32 v102, 0xbfb8aa3b, v90
	v_mul_f32_e32 v103, 0xbfb8aa3b, v91
	v_exp_f32_e32 v96, v96
	v_exp_f32_e32 v97, v97
	v_exp_f32_e32 v98, v98
	v_exp_f32_e32 v99, v99
	v_exp_f32_e32 v100, v100
	v_exp_f32_e32 v101, v101
	v_exp_f32_e32 v102, v102
	v_exp_f32_e32 v103, v103
	v_add_f32_e32 v96, 1.0, v96
	v_add_f32_e32 v97, 1.0, v97
	v_add_f32_e32 v98, 1.0, v98
	v_add_f32_e32 v99, 1.0, v99
	v_add_f32_e32 v100, 1.0, v100
	v_add_f32_e32 v101, 1.0, v101
	v_add_f32_e32 v102, 1.0, v102
	v_add_f32_e32 v103, 1.0, v103
	v_rcp_f32_e32 v96, v96
	v_rcp_f32_e32 v97, v97
	v_rcp_f32_e32 v98, v98
	v_rcp_f32_e32 v99, v99
	v_rcp_f32_e32 v100, v100
	v_rcp_f32_e32 v102, v102
	v_rcp_f32_e32 v103, v103
	v_rcp_f32_e32 v101, v101
	v_pk_mul_f32 v[98:99], v[94:95], v[98:99]
	v_pk_mul_f32 v[96:97], v[92:93], v[96:97]
	v_pk_mul_f32 v[102:103], v[90:91], v[102:103]
	v_pk_mul_f32 v[100:101], v[88:89], v[100:101]
	s_mov_b64 s[8:9], 0

; __device__ __forceinline__ u32x4 pack8(const float (&f)[8]) { u32x4 w; w.x = cvt_pk_bf16(f[0], f[1]); w.y = cvt_pk_bf16(f[2], f[3]); w.z = cvt_pk_bf16(f[4], f[5]); w.w = cvt_pk_bf16(f[6], f[7]); return w; }
; __device__ __forceinline__ float sigm(float x) { return __builtin_amdgcn_rcpf(1.f + __builtin_amdgcn_exp2f(-1.4426950408889634f * x)); }
;     __device__ __forceinline__ void operator()(const f32x4 (&acc)[2][2][4][2], const Unit& u, int wr, int wc, int fr, int fq) const {
;     ...
;         for (int ai = 0; ai < 2; ++ai)
; #pragma unroll
;             for (int m = 0; m < 4; ++m) { bf16_t* rowp = base + (size_t)(row0 + ai * HALF + m * 16) * ldc + col0;
; #pragma unroll
;                 for (int bj = 0; bj < 2; ++bj) { const f32x4 v0 = acc[ai][bj][m][0], v1 = acc[ai][bj][m][1];
;                     float f[8] = {v0[0], v0[1], v0[2], v0[3], v1[0], v1[1], v1[2], v1[3]};
;                     if (act == 1) {
; #pragma unroll
;                         for (int e = 0; e < 8; ++e) f[e] = sigm(f[e]);
;                     } else if (act == 2) {
; #pragma unroll
;                         for (int e = 0; e < 8; ++e) f[e] = f[e] * sigm(f[e]);
;                     }
;                     __builtin_nontemporal_store(pack8(f), (u32x4*)(rowp + bj * HALF)); } }
.LBB0_164:
	v_or_b32_e32 v88, 32, v160
	v_mul_lo_u32 v90, s79, v88
	v_mad_u64_u32 v[88:89], s[8:9], s78, v88, 0
	v_add3_u32 v89, v89, v136, v90
	v_lshl_add_u64 v[88:89], v[88:89], 1, v[120:121]
	v_cvt_pk_bf16_f32 v90, v96, v97
	v_cvt_pk_bf16_f32 v91, v98, v99
	v_cvt_pk_bf16_f32 v92, v100, v101
	v_cvt_pk_bf16_f32 v93, v102, v103
	s_and_b64 vcc, exec, s[6:7]
	s_mov_b64 s[8:9], -1
	ds_write_b128 v228, v[90:93]
	ds_read_b128 v[232:235], v229
	s_waitcnt lgkmcnt(0)
	global_store_dwordx4 v[88:89], v[232:235], off nt
	s_cbranch_vccnz .LBB0_167
	s_and_b64 vcc, exec, s[4:5]
	s_cbranch_vccnz .LBB0_227
	v_mul_f32_e32 v90, 0xbfb8aa3b, v84
	v_mul_f32_e32 v91, 0xbfb8aa3b, v85
	v_mul_f32_e32 v92, 0xbfb8aa3b, v86
	v_mul_f32_e32 v93, 0xbfb8aa3b, v87
	v_mul_f32_e32 v94, 0xbfb8aa3b, v80
	v_mul_f32_e32 v95, 0xbfb8aa3b, v81
	v_mul_f32_e32 v96, 0xbfb8aa3b, v82
	v_mul_f32_e32 v97, 0xbfb8aa3b, v83
	v_exp_f32_e32 v90, v90
	v_exp_f32_e32 v91, v91
	v_exp_f32_e32 v92, v92
	v_exp_f32_e32 v93, v93
	v_exp_f32_e32 v94, v94
	v_exp_f32_e32 v95, v95
	v_exp_f32_e32 v96, v96
	v_exp_f32_e32 v97, v97
	v_add_f32_e32 v90, 1.0, v90
	v_add_f32_e32 v91, 1.0, v91
	v_add_f32_e32 v92, 1.0, v92
	v_add_f32_e32 v93, 1.0, v93
	v_add_f32_e32 v94, 1.0, v94
	v_add_f32_e32 v95, 1.0, v95
	v_add_f32_e32 v96, 1.0, v96
	v_add_f32_e32 v97, 1.0, v97
	v_rcp_f32_e32 v90, v90
	v_rcp_f32_e32 v91, v91
	v_rcp_f32_e32 v92, v92
	v_rcp_f32_e32 v93, v93
	v_rcp_f32_e32 v94, v94
	v_rcp_f32_e32 v96, v96
	v_rcp_f32_e32 v97, v97
	v_rcp_f32_e32 v95, v95
	v_pk_mul_f32 v[92:93], v[86:87], v[92:93]
	v_pk_mul_f32 v[90:91], v[84:85], v[90:91]
	v_pk_mul_f32 v[96:97], v[82:83], v[96:97]
	v_pk_mul_f32 v[94:95], v[80:81], v[94:95]
	s_mov_b64 s[8:9], 0

; __device__ __forceinline__ u32x4 pack8(const float (&f)[8]) { u32x4 w; w.x = cvt_pk_bf16(f[0], f[1]); w.y = cvt_pk_bf16(f[2], f[3]); w.z = cvt_pk_bf16(f[4], f[5]); w.w = cvt_pk_bf16(f[6], f[7]); return w; }
; __device__ __forceinline__ float sigm(float x) { return __builtin_amdgcn_rcpf(1.f + __builtin_amdgcn_exp2f(-1.4426950408889634f * x)); }
;     __device__ __forceinline__ void operator()(const f32x4 (&acc)[2][2][4][2], const Unit& u, int wr, int wc, int fr, int fq) const {
;     ...
;         for (int ai = 0; ai < 2; ++ai)
; #pragma unroll
;             for (int m = 0; m < 4; ++m) { bf16_t* rowp = base + (size_t)(row0 + ai * HALF + m * 16) * ldc + col0;
; #pragma unroll
;                 for (int bj = 0; bj < 2; ++bj) { const f32x4 v0 = acc[ai][bj][m][0], v1 = acc[ai][bj][m][1];
;                     float f[8] = {v0[0], v0[1], v0[2], v0[3], v1[0], v1[1], v1[2], v1[3]};
;                     if (act == 1) {
; #pragma unroll
;                         for (int e = 0; e < 8; ++e) f[e] = sigm(f[e]);
;                     } else if (act == 2) {
; #pragma unroll
;                         for (int e = 0; e < 8; ++e) f[e] = f[e] * sigm(f[e]);
;                     }
;                     __builtin_nontemporal_store(pack8(f), (u32x4*)(rowp + bj * HALF)); } }
.LBB0_169:
	v_cvt_pk_bf16_f32 v80, v90, v91
	v_cvt_pk_bf16_f32 v81, v92, v93
	v_cvt_pk_bf16_f32 v82, v94, v95
	v_cvt_pk_bf16_f32 v83, v96, v97
	s_and_b64 vcc, exec, s[6:7]
	s_mov_b64 s[8:9], -1
	ds_write_b128 v228, v[80:83]
	ds_read_b128 v[232:235], v229
	s_waitcnt lgkmcnt(0)
	global_store_dwordx4 v[88:89], v[232:235], off offset:256 nt
	s_cbranch_vccnz .LBB0_172
	s_and_b64 vcc, exec, s[4:5]
	s_cbranch_vccnz .LBB0_228
	v_mul_f32_e32 v80, 0xbfb8aa3b, v76
	v_mul_f32_e32 v81, 0xbfb8aa3b, v77
	v_mul_f32_e32 v82, 0xbfb8aa3b, v78
	v_mul_f32_e32 v83, 0xbfb8aa3b, v79
	v_mul_f32_e32 v84, 0xbfb8aa3b, v72
	v_mul_f32_e32 v85, 0xbfb8aa3b, v73
	v_mul_f32_e32 v86, 0xbfb8aa3b, v74
	v_mul_f32_e32 v87, 0xbfb8aa3b, v75
	v_exp_f32_e32 v80, v80
	v_exp_f32_e32 v81, v81
	v_exp_f32_e32 v82, v82
	v_exp_f32_e32 v83, v83
	v_exp_f32_e32 v84, v84
	v_exp_f32_e32 v85, v85
	v_exp_f32_e32 v86, v86
	v_exp_f32_e32 v87, v87
	v_add_f32_e32 v80, 1.0, v80
	v_add_f32_e32 v81, 1.0, v81
	v_add_f32_e32 v82, 1.0, v82
	v_add_f32_e32 v83, 1.0, v83
	v_add_f32_e32 v84, 1.0, v84
	v_add_f32_e32 v85, 1.0, v85
	v_add_f32_e32 v86, 1.0, v86
	v_add_f32_e32 v87, 1.0, v87
	v_rcp_f32_e32 v80, v80
	v_rcp_f32_e32 v81, v81
	v_rcp_f32_e32 v82, v82
	v_rcp_f32_e32 v83, v83
	v_rcp_f32_e32 v84, v84
	v_rcp_f32_e32 v86, v86
	v_rcp_f32_e32 v87, v87
	v_rcp_f32_e32 v85, v85
	v_pk_mul_f32 v[82:83], v[78:79], v[82:83]
	v_pk_mul_f32 v[80:81], v[76:77], v[80:81]
	v_pk_mul_f32 v[86:87], v[74:75], v[86:87]
	v_pk_mul_f32 v[84:85], v[72:73], v[84:85]
	s_mov_b64 s[8:9], 0

; __device__ __forceinline__ u32x4 pack8(const float (&f)[8]) { u32x4 w; w.x = cvt_pk_bf16(f[0], f[1]); w.y = cvt_pk_bf16(f[2], f[3]); w.z = cvt_pk_bf16(f[4], f[5]); w.w = cvt_pk_bf16(f[6], f[7]); return w; }
; __device__ __forceinline__ float sigm(float x) { return __builtin_amdgcn_rcpf(1.f + __builtin_amdgcn_exp2f(-1.4426950408889634f * x)); }
;     __device__ __forceinline__ void operator()(const f32x4 (&acc)[2][2][4][2], const Unit& u, int wr, int wc, int fr, int fq) const {
;     ...
;         for (int ai = 0; ai < 2; ++ai)
; #pragma unroll
;             for (int m = 0; m < 4; ++m) { bf16_t* rowp = base + (size_t)(row0 + ai * HALF + m * 16) * ldc + col0;
; #pragma unroll
;                 for (int bj = 0; bj < 2; ++bj) { const f32x4 v0 = acc[ai][bj][m][0], v1 = acc[ai][bj][m][1];
;                     float f[8] = {v0[0], v0[1], v0[2], v0[3], v1[0], v1[1], v1[2], v1[3]};
;                     if (act == 1) {
; #pragma unroll
;                         for (int e = 0; e < 8; ++e) f[e] = sigm(f[e]);
;                     } else if (act == 2) {
; #pragma unroll
;                         for (int e = 0; e < 8; ++e) f[e] = f[e] * sigm(f[e]);
;                     }
;                     __builtin_nontemporal_store(pack8(f), (u32x4*)(rowp + bj * HALF)); } }
.LBB0_174:
	v_or_b32_e32 v72, 48, v160
	v_mul_lo_u32 v74, s79, v72
	v_mad_u64_u32 v[72:73], s[8:9], s78, v72, 0
	v_add3_u32 v73, v73, v136, v74
	v_lshl_add_u64 v[72:73], v[72:73], 1, v[120:121]
	v_cvt_pk_bf16_f32 v74, v80, v81
	v_cvt_pk_bf16_f32 v75, v82, v83
	v_cvt_pk_bf16_f32 v76, v84, v85
	v_cvt_pk_bf16_f32 v77, v86, v87
	s_and_b64 vcc, exec, s[6:7]
	s_mov_b64 s[8:9], -1
	ds_write_b128 v228, v[74:77]
	ds_read_b128 v[232:235], v229
	s_waitcnt lgkmcnt(0)
	global_store_dwordx4 v[72:73], v[232:235], off nt
	s_cbranch_vccnz .LBB0_177
	s_and_b64 vcc, exec, s[4:5]
	s_cbranch_vccnz .LBB0_229
	v_mul_f32_e32 v74, 0xbfb8aa3b, v68
	v_mul_f32_e32 v75, 0xbfb8aa3b, v69
	v_mul_f32_e32 v76, 0xbfb8aa3b, v70
	v_mul_f32_e32 v77, 0xbfb8aa3b, v71
	v_mul_f32_e32 v78, 0xbfb8aa3b, v64
	v_mul_f32_e32 v79, 0xbfb8aa3b, v65
	v_mul_f32_e32 v80, 0xbfb8aa3b, v66
	v_mul_f32_e32 v81, 0xbfb8aa3b, v67
	v_exp_f32_e32 v74, v74
	v_exp_f32_e32 v75, v75
	v_exp_f32_e32 v76, v76
	v_exp_f32_e32 v77, v77
	v_exp_f32_e32 v78, v78
	v_exp_f32_e32 v79, v79
	v_exp_f32_e32 v80, v80
	v_exp_f32_e32 v81, v81
	v_add_f32_e32 v74, 1.0, v74
	v_add_f32_e32 v75, 1.0, v75
	v_add_f32_e32 v76, 1.0, v76
	v_add_f32_e32 v77, 1.0, v77
	v_add_f32_e32 v78, 1.0, v78
	v_add_f32_e32 v79, 1.0, v79
	v_add_f32_e32 v80, 1.0, v80
	v_add_f32_e32 v81, 1.0, v81
	v_rcp_f32_e32 v74, v74
	v_rcp_f32_e32 v75, v75
	v_rcp_f32_e32 v76, v76
	v_rcp_f32_e32 v77, v77
	v_rcp_f32_e32 v78, v78
	v_rcp_f32_e32 v80, v80
	v_rcp_f32_e32 v81, v81
	v_rcp_f32_e32 v79, v79
	v_pk_mul_f32 v[76:77], v[70:71], v[76:77]
	v_pk_mul_f32 v[74:75], v[68:69], v[74:75]
	v_pk_mul_f32 v[80:81], v[66:67], v[80:81]
	v_pk_mul_f32 v[78:79], v[64:65], v[78:79]
	s_mov_b64 s[8:9], 0

; __device__ __forceinline__ u32x4 pack8(const float (&f)[8]) { u32x4 w; w.x = cvt_pk_bf16(f[0], f[1]); w.y = cvt_pk_bf16(f[2], f[3]); w.z = cvt_pk_bf16(f[4], f[5]); w.w = cvt_pk_bf16(f[6], f[7]); return w; }
; __device__ __forceinline__ float sigm(float x) { return __builtin_amdgcn_rcpf(1.f + __builtin_amdgcn_exp2f(-1.4426950408889634f * x)); }
;     __device__ __forceinline__ void operator()(const f32x4 (&acc)[2][2][4][2], const Unit& u, int wr, int wc, int fr, int fq) const {
;     ...
;         for (int ai = 0; ai < 2; ++ai)
; #pragma unroll
;             for (int m = 0; m < 4; ++m) { bf16_t* rowp = base + (size_t)(row0 + ai * HALF + m * 16) * ldc + col0;
; #pragma unroll
;                 for (int bj = 0; bj < 2; ++bj) { const f32x4 v0 = acc[ai][bj][m][0], v1 = acc[ai][bj][m][1];
;                     float f[8] = {v0[0], v0[1], v0[2], v0[3], v1[0], v1[1], v1[2], v1[3]};
;                     if (act == 1) {
; #pragma unroll
;                         for (int e = 0; e < 8; ++e) f[e] = sigm(f[e]);
;                     } else if (act == 2) {
; #pragma unroll
;                         for (int e = 0; e < 8; ++e) f[e] = f[e] * sigm(f[e]);
;                     }
;                     __builtin_nontemporal_store(pack8(f), (u32x4*)(rowp + bj * HALF)); } }
.LBB0_179:
	v_cvt_pk_bf16_f32 v64, v74, v75
	v_cvt_pk_bf16_f32 v65, v76, v77
	v_cvt_pk_bf16_f32 v66, v78, v79
	v_cvt_pk_bf16_f32 v67, v80, v81
	s_and_b64 vcc, exec, s[6:7]
	s_mov_b64 s[8:9], -1
	ds_write_b128 v228, v[64:67]
	ds_read_b128 v[232:235], v229
	s_waitcnt lgkmcnt(0)
	global_store_dwordx4 v[72:73], v[232:235], off offset:256 nt
	s_cbranch_vccnz .LBB0_182
	s_and_b64 vcc, exec, s[4:5]
	s_cbranch_vccnz .LBB0_230
	v_mul_f32_e32 v64, 0xbfb8aa3b, v60
	v_mul_f32_e32 v65, 0xbfb8aa3b, v61
	v_mul_f32_e32 v66, 0xbfb8aa3b, v62
	v_mul_f32_e32 v67, 0xbfb8aa3b, v63
	v_mul_f32_e32 v68, 0xbfb8aa3b, v56
	v_mul_f32_e32 v69, 0xbfb8aa3b, v57
	v_mul_f32_e32 v70, 0xbfb8aa3b, v58
	v_mul_f32_e32 v71, 0xbfb8aa3b, v59
	v_exp_f32_e32 v64, v64
	v_exp_f32_e32 v65, v65
	v_exp_f32_e32 v66, v66
	v_exp_f32_e32 v67, v67
	v_exp_f32_e32 v68, v68
	v_exp_f32_e32 v69, v69
	v_exp_f32_e32 v70, v70
	v_exp_f32_e32 v71, v71
	v_add_f32_e32 v64, 1.0, v64
	v_add_f32_e32 v65, 1.0, v65
	v_add_f32_e32 v66, 1.0, v66
	v_add_f32_e32 v67, 1.0, v67
	v_add_f32_e32 v68, 1.0, v68
	v_add_f32_e32 v69, 1.0, v69
	v_add_f32_e32 v70, 1.0, v70
	v_add_f32_e32 v71, 1.0, v71
	v_rcp_f32_e32 v64, v64
	v_rcp_f32_e32 v65, v65
	v_rcp_f32_e32 v66, v66
	v_rcp_f32_e32 v67, v67
	v_rcp_f32_e32 v68, v68
	v_rcp_f32_e32 v70, v70
	v_rcp_f32_e32 v71, v71
	v_rcp_f32_e32 v69, v69
	v_pk_mul_f32 v[66:67], v[62:63], v[66:67]
	v_pk_mul_f32 v[64:65], v[60:61], v[64:65]
	v_pk_mul_f32 v[70:71], v[58:59], v[70:71]
	v_pk_mul_f32 v[68:69], v[56:57], v[68:69]
	s_mov_b64 s[8:9], 0

; __device__ __forceinline__ u32x4 pack8(const float (&f)[8]) { u32x4 w; w.x = cvt_pk_bf16(f[0], f[1]); w.y = cvt_pk_bf16(f[2], f[3]); w.z = cvt_pk_bf16(f[4], f[5]); w.w = cvt_pk_bf16(f[6], f[7]); return w; }
; __device__ __forceinline__ float sigm(float x) { return __builtin_amdgcn_rcpf(1.f + __builtin_amdgcn_exp2f(-1.4426950408889634f * x)); }
;     __device__ __forceinline__ void operator()(const f32x4 (&acc)[2][2][4][2], const Unit& u, int wr, int wc, int fr, int fq) const {
;     ...
;         for (int ai = 0; ai < 2; ++ai)
; #pragma unroll
;             for (int m = 0; m < 4; ++m) { bf16_t* rowp = base + (size_t)(row0 + ai * HALF + m * 16) * ldc + col0;
; #pragma unroll
;                 for (int bj = 0; bj < 2; ++bj) { const f32x4 v0 = acc[ai][bj][m][0], v1 = acc[ai][bj][m][1];
;                     float f[8] = {v0[0], v0[1], v0[2], v0[3], v1[0], v1[1], v1[2], v1[3]};
;                     if (act == 1) {
; #pragma unroll
;                         for (int e = 0; e < 8; ++e) f[e] = sigm(f[e]);
;                     } else if (act == 2) {
; #pragma unroll
;                         for (int e = 0; e < 8; ++e) f[e] = f[e] * sigm(f[e]);
;                     }
;                     __builtin_nontemporal_store(pack8(f), (u32x4*)(rowp + bj * HALF)); } }
.LBB0_184:
	v_add_u32_e32 v56, 0x80, v160
	v_ashrrev_i32_e32 v57, 31, v56
	v_mul_lo_u32 v58, s78, v57
	v_mul_lo_u32 v59, s79, v56
	v_mad_u64_u32 v[56:57], s[8:9], s78, v56, 0
	v_add3_u32 v57, v57, v58, v59
	v_lshl_add_u64 v[56:57], v[56:57], 1, v[120:121]
	v_cvt_pk_bf16_f32 v58, v64, v65
	v_cvt_pk_bf16_f32 v59, v66, v67
	v_cvt_pk_bf16_f32 v60, v68, v69
	v_cvt_pk_bf16_f32 v61, v70, v71
	s_and_b64 vcc, exec, s[6:7]
	s_mov_b64 s[8:9], -1
	ds_write_b128 v228, v[58:61]
	ds_read_b128 v[232:235], v229
	s_waitcnt lgkmcnt(0)
	global_store_dwordx4 v[56:57], v[232:235], off nt
	s_cbranch_vccnz .LBB0_187
	s_and_b64 vcc, exec, s[4:5]
	s_cbranch_vccnz .LBB0_231
	v_mul_f32_e32 v58, 0xbfb8aa3b, v52
	v_mul_f32_e32 v59, 0xbfb8aa3b, v53
	v_mul_f32_e32 v60, 0xbfb8aa3b, v54
	v_mul_f32_e32 v61, 0xbfb8aa3b, v55
	v_mul_f32_e32 v62, 0xbfb8aa3b, v48
	v_mul_f32_e32 v63, 0xbfb8aa3b, v49
	v_mul_f32_e32 v64, 0xbfb8aa3b, v50
	v_mul_f32_e32 v65, 0xbfb8aa3b, v51
	v_exp_f32_e32 v58, v58
	v_exp_f32_e32 v59, v59
	v_exp_f32_e32 v60, v60
	v_exp_f32_e32 v61, v61
	v_exp_f32_e32 v62, v62
	v_exp_f32_e32 v63, v63
	v_exp_f32_e32 v64, v64
	v_exp_f32_e32 v65, v65
	v_add_f32_e32 v58, 1.0, v58
	v_add_f32_e32 v59, 1.0, v59
	v_add_f32_e32 v60, 1.0, v60
	v_add_f32_e32 v61, 1.0, v61
	v_add_f32_e32 v62, 1.0, v62
	v_add_f32_e32 v63, 1.0, v63
	v_add_f32_e32 v64, 1.0, v64
	v_add_f32_e32 v65, 1.0, v65
	v_rcp_f32_e32 v58, v58
	v_rcp_f32_e32 v59, v59
	v_rcp_f32_e32 v60, v60
	v_rcp_f32_e32 v61, v61
	v_rcp_f32_e32 v62, v62
	v_rcp_f32_e32 v64, v64
	v_rcp_f32_e32 v65, v65
	v_rcp_f32_e32 v63, v63
	v_pk_mul_f32 v[60:61], v[54:55], v[60:61]
	v_pk_mul_f32 v[58:59], v[52:53], v[58:59]
	v_pk_mul_f32 v[64:65], v[50:51], v[64:65]
	v_pk_mul_f32 v[62:63], v[48:49], v[62:63]
	s_mov_b64 s[8:9], 0

; __device__ __forceinline__ u32x4 pack8(const float (&f)[8]) { u32x4 w; w.x = cvt_pk_bf16(f[0], f[1]); w.y = cvt_pk_bf16(f[2], f[3]); w.z = cvt_pk_bf16(f[4], f[5]); w.w = cvt_pk_bf16(f[6], f[7]); return w; }
; __device__ __forceinline__ float sigm(float x) { return __builtin_amdgcn_rcpf(1.f + __builtin_amdgcn_exp2f(-1.4426950408889634f * x)); }
;     __device__ __forceinline__ void operator()(const f32x4 (&acc)[2][2][4][2], const Unit& u, int wr, int wc, int fr, int fq) const {
;     ...
;         for (int ai = 0; ai < 2; ++ai)
; #pragma unroll
;             for (int m = 0; m < 4; ++m) { bf16_t* rowp = base + (size_t)(row0 + ai * HALF + m * 16) * ldc + col0;
; #pragma unroll
;                 for (int bj = 0; bj < 2; ++bj) { const f32x4 v0 = acc[ai][bj][m][0], v1 = acc[ai][bj][m][1];
;                     float f[8] = {v0[0], v0[1], v0[2], v0[3], v1[0], v1[1], v1[2], v1[3]};
;                     if (act == 1) {
; #pragma unroll
;                         for (int e = 0; e < 8; ++e) f[e] = sigm(f[e]);
;                     } else if (act == 2) {
; #pragma unroll
;                         for (int e = 0; e < 8; ++e) f[e] = f[e] * sigm(f[e]);
;                     }
;                     __builtin_nontemporal_store(pack8(f), (u32x4*)(rowp + bj * HALF)); } }
.LBB0_189:
	v_cvt_pk_bf16_f32 v48, v58, v59
	v_cvt_pk_bf16_f32 v49, v60, v61
	v_cvt_pk_bf16_f32 v50, v62, v63
	v_cvt_pk_bf16_f32 v51, v64, v65
	s_and_b64 vcc, exec, s[6:7]
	s_mov_b64 s[8:9], -1
	ds_write_b128 v228, v[48:51]
	ds_read_b128 v[232:235], v229
	s_waitcnt lgkmcnt(0)
	global_store_dwordx4 v[56:57], v[232:235], off offset:256 nt
	s_cbranch_vccnz .LBB0_192
	s_and_b64 vcc, exec, s[4:5]
	s_cbranch_vccnz .LBB0_232
	v_mul_f32_e32 v48, 0xbfb8aa3b, v44
	v_mul_f32_e32 v49, 0xbfb8aa3b, v45
	v_mul_f32_e32 v50, 0xbfb8aa3b, v46
	v_mul_f32_e32 v51, 0xbfb8aa3b, v47
	v_mul_f32_e32 v52, 0xbfb8aa3b, v40
	v_mul_f32_e32 v53, 0xbfb8aa3b, v41
	v_mul_f32_e32 v54, 0xbfb8aa3b, v42
	v_mul_f32_e32 v55, 0xbfb8aa3b, v43
	v_exp_f32_e32 v48, v48
	v_exp_f32_e32 v49, v49
	v_exp_f32_e32 v50, v50
	v_exp_f32_e32 v51, v51
	v_exp_f32_e32 v52, v52
	v_exp_f32_e32 v53, v53
	v_exp_f32_e32 v54, v54
	v_exp_f32_e32 v55, v55
	v_add_f32_e32 v48, 1.0, v48
	v_add_f32_e32 v49, 1.0, v49
	v_add_f32_e32 v50, 1.0, v50
	v_add_f32_e32 v51, 1.0, v51
	v_add_f32_e32 v52, 1.0, v52
	v_add_f32_e32 v53, 1.0, v53
	v_add_f32_e32 v54, 1.0, v54
	v_add_f32_e32 v55, 1.0, v55
	v_rcp_f32_e32 v48, v48
	v_rcp_f32_e32 v49, v49
	v_rcp_f32_e32 v50, v50
	v_rcp_f32_e32 v51, v51
	v_rcp_f32_e32 v52, v52
	v_rcp_f32_e32 v54, v54
	v_rcp_f32_e32 v55, v55
	v_rcp_f32_e32 v53, v53
	v_pk_mul_f32 v[50:51], v[46:47], v[50:51]
	v_pk_mul_f32 v[48:49], v[44:45], v[48:49]
	v_pk_mul_f32 v[54:55], v[42:43], v[54:55]
	v_pk_mul_f32 v[52:53], v[40:41], v[52:53]
	s_mov_b64 s[8:9], 0

; __device__ __forceinline__ u32x4 pack8(const float (&f)[8]) { u32x4 w; w.x = cvt_pk_bf16(f[0], f[1]); w.y = cvt_pk_bf16(f[2], f[3]); w.z = cvt_pk_bf16(f[4], f[5]); w.w = cvt_pk_bf16(f[6], f[7]); return w; }
; __device__ __forceinline__ float sigm(float x) { return __builtin_amdgcn_rcpf(1.f + __builtin_amdgcn_exp2f(-1.4426950408889634f * x)); }
;     __device__ __forceinline__ void operator()(const f32x4 (&acc)[2][2][4][2], const Unit& u, int wr, int wc, int fr, int fq) const {
;     ...
;         for (int ai = 0; ai < 2; ++ai)
; #pragma unroll
;             for (int m = 0; m < 4; ++m) { bf16_t* rowp = base + (size_t)(row0 + ai * HALF + m * 16) * ldc + col0;
; #pragma unroll
;                 for (int bj = 0; bj < 2; ++bj) { const f32x4 v0 = acc[ai][bj][m][0], v1 = acc[ai][bj][m][1];
;                     float f[8] = {v0[0], v0[1], v0[2], v0[3], v1[0], v1[1], v1[2], v1[3]};
;                     if (act == 1) {
; #pragma unroll
;                         for (int e = 0; e < 8; ++e) f[e] = sigm(f[e]);
;                     } else if (act == 2) {
; #pragma unroll
;                         for (int e = 0; e < 8; ++e) f[e] = f[e] * sigm(f[e]);
;                     }
;                     __builtin_nontemporal_store(pack8(f), (u32x4*)(rowp + bj * HALF)); } }
.LBB0_194:
	v_add_u32_e32 v40, 0x90, v160
	v_ashrrev_i32_e32 v41, 31, v40
	v_mul_lo_u32 v42, s78, v41
	v_mul_lo_u32 v43, s79, v40
	v_mad_u64_u32 v[40:41], s[8:9], s78, v40, 0
	v_add3_u32 v41, v41, v42, v43
	v_lshl_add_u64 v[40:41], v[40:41], 1, v[120:121]
	v_cvt_pk_bf16_f32 v42, v48, v49
	v_cvt_pk_bf16_f32 v43, v50, v51
	v_cvt_pk_bf16_f32 v44, v52, v53
	v_cvt_pk_bf16_f32 v45, v54, v55
	s_and_b64 vcc, exec, s[6:7]
	s_mov_b64 s[8:9], -1
	ds_write_b128 v228, v[42:45]
	ds_read_b128 v[232:235], v229
	s_waitcnt lgkmcnt(0)
	global_store_dwordx4 v[40:41], v[232:235], off nt
	s_cbranch_vccnz .LBB0_197
	s_and_b64 vcc, exec, s[4:5]
	s_cbranch_vccnz .LBB0_233
	v_mul_f32_e32 v42, 0xbfb8aa3b, v36
	v_mul_f32_e32 v43, 0xbfb8aa3b, v37
	v_mul_f32_e32 v44, 0xbfb8aa3b, v38
	v_mul_f32_e32 v45, 0xbfb8aa3b, v39
	v_mul_f32_e32 v46, 0xbfb8aa3b, v32
	v_mul_f32_e32 v47, 0xbfb8aa3b, v33
	v_mul_f32_e32 v48, 0xbfb8aa3b, v34
	v_mul_f32_e32 v49, 0xbfb8aa3b, v35
	v_exp_f32_e32 v42, v42
	v_exp_f32_e32 v43, v43
	v_exp_f32_e32 v44, v44
	v_exp_f32_e32 v45, v45
	v_exp_f32_e32 v46, v46
	v_exp_f32_e32 v47, v47
	v_exp_f32_e32 v48, v48
	v_exp_f32_e32 v49, v49
	v_add_f32_e32 v42, 1.0, v42
	v_add_f32_e32 v43, 1.0, v43
	v_add_f32_e32 v44, 1.0, v44
	v_add_f32_e32 v45, 1.0, v45
	v_add_f32_e32 v46, 1.0, v46
	v_add_f32_e32 v47, 1.0, v47
	v_add_f32_e32 v48, 1.0, v48
	v_add_f32_e32 v49, 1.0, v49
	v_rcp_f32_e32 v42, v42
	v_rcp_f32_e32 v43, v43
	v_rcp_f32_e32 v44, v44
	v_rcp_f32_e32 v45, v45
	v_rcp_f32_e32 v46, v46
	v_rcp_f32_e32 v48, v48
	v_rcp_f32_e32 v49, v49
	v_rcp_f32_e32 v47, v47
	v_pk_mul_f32 v[44:45], v[38:39], v[44:45]
	v_pk_mul_f32 v[42:43], v[36:37], v[42:43]
	v_pk_mul_f32 v[48:49], v[34:35], v[48:49]
	v_pk_mul_f32 v[46:47], v[32:33], v[46:47]
	s_mov_b64 s[8:9], 0

; __device__ __forceinline__ u32x4 pack8(const float (&f)[8]) { u32x4 w; w.x = cvt_pk_bf16(f[0], f[1]); w.y = cvt_pk_bf16(f[2], f[3]); w.z = cvt_pk_bf16(f[4], f[5]); w.w = cvt_pk_bf16(f[6], f[7]); return w; }
; __device__ __forceinline__ float sigm(float x) { return __builtin_amdgcn_rcpf(1.f + __builtin_amdgcn_exp2f(-1.4426950408889634f * x)); }
;     __device__ __forceinline__ void operator()(const f32x4 (&acc)[2][2][4][2], const Unit& u, int wr, int wc, int fr, int fq) const {
;     ...
;         for (int ai = 0; ai < 2; ++ai)
; #pragma unroll
;             for (int m = 0; m < 4; ++m) { bf16_t* rowp = base + (size_t)(row0 + ai * HALF + m * 16) * ldc + col0;
; #pragma unroll
;                 for (int bj = 0; bj < 2; ++bj) { const f32x4 v0 = acc[ai][bj][m][0], v1 = acc[ai][bj][m][1];
;                     float f[8] = {v0[0], v0[1], v0[2], v0[3], v1[0], v1[1], v1[2], v1[3]};
;                     if (act == 1) {
; #pragma unroll
;                         for (int e = 0; e < 8; ++e) f[e] = sigm(f[e]);
;                     } else if (act == 2) {
; #pragma unroll
;                         for (int e = 0; e < 8; ++e) f[e] = f[e] * sigm(f[e]);
;                     }
;                     __builtin_nontemporal_store(pack8(f), (u32x4*)(rowp + bj * HALF)); } }
.LBB0_199:
	v_cvt_pk_bf16_f32 v32, v42, v43
	v_cvt_pk_bf16_f32 v33, v44, v45
	v_cvt_pk_bf16_f32 v34, v46, v47
	v_cvt_pk_bf16_f32 v35, v48, v49
	s_and_b64 vcc, exec, s[6:7]
	s_mov_b64 s[8:9], -1
	ds_write_b128 v228, v[32:35]
	ds_read_b128 v[232:235], v229
	s_waitcnt lgkmcnt(0)
	global_store_dwordx4 v[40:41], v[232:235], off offset:256 nt
	s_cbranch_vccnz .LBB0_202
	s_and_b64 vcc, exec, s[4:5]
	s_cbranch_vccnz .LBB0_234
	v_mul_f32_e32 v32, 0xbfb8aa3b, v28
	v_mul_f32_e32 v33, 0xbfb8aa3b, v29
	v_mul_f32_e32 v34, 0xbfb8aa3b, v30
	v_mul_f32_e32 v35, 0xbfb8aa3b, v31
	v_mul_f32_e32 v36, 0xbfb8aa3b, v24
	v_mul_f32_e32 v37, 0xbfb8aa3b, v25
	v_mul_f32_e32 v38, 0xbfb8aa3b, v26
	v_mul_f32_e32 v39, 0xbfb8aa3b, v27
	v_exp_f32_e32 v32, v32
	v_exp_f32_e32 v33, v33
	v_exp_f32_e32 v34, v34
	v_exp_f32_e32 v35, v35
	v_exp_f32_e32 v36, v36
	v_exp_f32_e32 v37, v37
	v_exp_f32_e32 v38, v38
	v_exp_f32_e32 v39, v39
	v_add_f32_e32 v32, 1.0, v32
	v_add_f32_e32 v33, 1.0, v33
	v_add_f32_e32 v34, 1.0, v34
	v_add_f32_e32 v35, 1.0, v35
	v_add_f32_e32 v36, 1.0, v36
	v_add_f32_e32 v37, 1.0, v37
	v_add_f32_e32 v38, 1.0, v38
	v_add_f32_e32 v39, 1.0, v39
	v_rcp_f32_e32 v32, v32
	v_rcp_f32_e32 v33, v33
	v_rcp_f32_e32 v34, v34
	v_rcp_f32_e32 v35, v35
	v_rcp_f32_e32 v36, v36
	v_rcp_f32_e32 v38, v38
	v_rcp_f32_e32 v39, v39
	v_rcp_f32_e32 v37, v37
	v_pk_mul_f32 v[34:35], v[30:31], v[34:35]
	v_pk_mul_f32 v[32:33], v[28:29], v[32:33]
	v_pk_mul_f32 v[38:39], v[26:27], v[38:39]
	v_pk_mul_f32 v[36:37], v[24:25], v[36:37]
	s_mov_b64 s[8:9], 0

; __device__ __forceinline__ u32x4 pack8(const float (&f)[8]) { u32x4 w; w.x = cvt_pk_bf16(f[0], f[1]); w.y = cvt_pk_bf16(f[2], f[3]); w.z = cvt_pk_bf16(f[4], f[5]); w.w = cvt_pk_bf16(f[6], f[7]); return w; }
; __device__ __forceinline__ float sigm(float x) { return __builtin_amdgcn_rcpf(1.f + __builtin_amdgcn_exp2f(-1.4426950408889634f * x)); }
;     __device__ __forceinline__ void operator()(const f32x4 (&acc)[2][2][4][2], const Unit& u, int wr, int wc, int fr, int fq) const {
;     ...
;         for (int ai = 0; ai < 2; ++ai)
; #pragma unroll
;             for (int m = 0; m < 4; ++m) { bf16_t* rowp = base + (size_t)(row0 + ai * HALF + m * 16) * ldc + col0;
; #pragma unroll
;                 for (int bj = 0; bj < 2; ++bj) { const f32x4 v0 = acc[ai][bj][m][0], v1 = acc[ai][bj][m][1];
;                     float f[8] = {v0[0], v0[1], v0[2], v0[3], v1[0], v1[1], v1[2], v1[3]};
;                     if (act == 1) {
; #pragma unroll
;                         for (int e = 0; e < 8; ++e) f[e] = sigm(f[e]);
;                     } else if (act == 2) {
; #pragma unroll
;                         for (int e = 0; e < 8; ++e) f[e] = f[e] * sigm(f[e]);
;                     }
;                     __builtin_nontemporal_store(pack8(f), (u32x4*)(rowp + bj * HALF)); } }
.LBB0_204:
	v_add_u32_e32 v24, 0xa0, v160
	v_ashrrev_i32_e32 v25, 31, v24
	v_mul_lo_u32 v26, s78, v25
	v_mul_lo_u32 v27, s79, v24
	v_mad_u64_u32 v[24:25], s[8:9], s78, v24, 0
	v_add3_u32 v25, v25, v26, v27
	v_lshl_add_u64 v[24:25], v[24:25], 1, v[120:121]
	v_cvt_pk_bf16_f32 v26, v32, v33
	v_cvt_pk_bf16_f32 v27, v34, v35
	v_cvt_pk_bf16_f32 v28, v36, v37
	v_cvt_pk_bf16_f32 v29, v38, v39
	s_and_b64 vcc, exec, s[6:7]
	s_mov_b64 s[8:9], -1
	ds_write_b128 v228, v[26:29]
	ds_read_b128 v[232:235], v229
	s_waitcnt lgkmcnt(0)
	global_store_dwordx4 v[24:25], v[232:235], off nt
	s_cbranch_vccnz .LBB0_207
	s_and_b64 vcc, exec, s[4:5]
	s_cbranch_vccnz .LBB0_235
	v_mul_f32_e32 v26, 0xbfb8aa3b, v20
	v_mul_f32_e32 v27, 0xbfb8aa3b, v21
	v_mul_f32_e32 v28, 0xbfb8aa3b, v22
	v_mul_f32_e32 v29, 0xbfb8aa3b, v23
	v_mul_f32_e32 v30, 0xbfb8aa3b, v16
	v_mul_f32_e32 v31, 0xbfb8aa3b, v17
	v_mul_f32_e32 v32, 0xbfb8aa3b, v18
	v_mul_f32_e32 v33, 0xbfb8aa3b, v19
	v_exp_f32_e32 v26, v26
	v_exp_f32_e32 v27, v27
	v_exp_f32_e32 v28, v28
	v_exp_f32_e32 v29, v29
	v_exp_f32_e32 v30, v30
	v_exp_f32_e32 v31, v31
	v_exp_f32_e32 v32, v32
	v_exp_f32_e32 v33, v33
	v_add_f32_e32 v26, 1.0, v26
	v_add_f32_e32 v27, 1.0, v27
	v_add_f32_e32 v28, 1.0, v28
	v_add_f32_e32 v29, 1.0, v29
	v_add_f32_e32 v30, 1.0, v30
	v_add_f32_e32 v31, 1.0, v31
	v_add_f32_e32 v32, 1.0, v32
	v_add_f32_e32 v33, 1.0, v33
	v_rcp_f32_e32 v26, v26
	v_rcp_f32_e32 v27, v27
	v_rcp_f32_e32 v28, v28
	v_rcp_f32_e32 v29, v29
	v_rcp_f32_e32 v30, v30
	v_rcp_f32_e32 v32, v32
	v_rcp_f32_e32 v33, v33
	v_rcp_f32_e32 v31, v31
	v_pk_mul_f32 v[28:29], v[22:23], v[28:29]
	v_pk_mul_f32 v[26:27], v[20:21], v[26:27]
	v_pk_mul_f32 v[32:33], v[18:19], v[32:33]
	v_pk_mul_f32 v[30:31], v[16:17], v[30:31]
	s_mov_b64 s[8:9], 0

; __device__ __forceinline__ u32x4 pack8(const float (&f)[8]) { u32x4 w; w.x = cvt_pk_bf16(f[0], f[1]); w.y = cvt_pk_bf16(f[2], f[3]); w.z = cvt_pk_bf16(f[4], f[5]); w.w = cvt_pk_bf16(f[6], f[7]); return w; }
; __device__ __forceinline__ float sigm(float x) { return __builtin_amdgcn_rcpf(1.f + __builtin_amdgcn_exp2f(-1.4426950408889634f * x)); }
;     __device__ __forceinline__ void operator()(const f32x4 (&acc)[2][2][4][2], const Unit& u, int wr, int wc, int fr, int fq) const {
;     ...
;         for (int ai = 0; ai < 2; ++ai)
; #pragma unroll
;             for (int m = 0; m < 4; ++m) { bf16_t* rowp = base + (size_t)(row0 + ai * HALF + m * 16) * ldc + col0;
; #pragma unroll
;                 for (int bj = 0; bj < 2; ++bj) { const f32x4 v0 = acc[ai][bj][m][0], v1 = acc[ai][bj][m][1];
;                     float f[8] = {v0[0], v0[1], v0[2], v0[3], v1[0], v1[1], v1[2], v1[3]};
;                     if (act == 1) {
; #pragma unroll
;                         for (int e = 0; e < 8; ++e) f[e] = sigm(f[e]);
;                     } else if (act == 2) {
; #pragma unroll
;                         for (int e = 0; e < 8; ++e) f[e] = f[e] * sigm(f[e]);
;                     }
;                     __builtin_nontemporal_store(pack8(f), (u32x4*)(rowp + bj * HALF)); } }
.LBB0_209:
	v_cvt_pk_bf16_f32 v16, v26, v27
	v_cvt_pk_bf16_f32 v17, v28, v29
	v_cvt_pk_bf16_f32 v18, v30, v31
	v_cvt_pk_bf16_f32 v19, v32, v33
	s_and_b64 vcc, exec, s[6:7]
	s_mov_b64 s[8:9], -1
	ds_write_b128 v228, v[16:19]
	ds_read_b128 v[232:235], v229
	s_waitcnt lgkmcnt(0)
	global_store_dwordx4 v[24:25], v[232:235], off offset:256 nt
	s_cbranch_vccnz .LBB0_212
	s_and_b64 vcc, exec, s[4:5]
	s_cbranch_vccnz .LBB0_236
	v_mul_f32_e32 v16, 0xbfb8aa3b, v12
	v_mul_f32_e32 v17, 0xbfb8aa3b, v13
	v_mul_f32_e32 v18, 0xbfb8aa3b, v14
	v_mul_f32_e32 v19, 0xbfb8aa3b, v15
	v_mul_f32_e32 v20, 0xbfb8aa3b, v8
	v_mul_f32_e32 v21, 0xbfb8aa3b, v9
	v_mul_f32_e32 v22, 0xbfb8aa3b, v10
	v_mul_f32_e32 v23, 0xbfb8aa3b, v11
	v_exp_f32_e32 v16, v16
	v_exp_f32_e32 v17, v17
	v_exp_f32_e32 v18, v18
	v_exp_f32_e32 v19, v19
	v_exp_f32_e32 v20, v20
	v_exp_f32_e32 v21, v21
	v_exp_f32_e32 v22, v22
	v_exp_f32_e32 v23, v23
	v_add_f32_e32 v16, 1.0, v16
	v_add_f32_e32 v17, 1.0, v17
	v_add_f32_e32 v18, 1.0, v18
	v_add_f32_e32 v19, 1.0, v19
	v_add_f32_e32 v20, 1.0, v20
	v_add_f32_e32 v21, 1.0, v21
	v_add_f32_e32 v22, 1.0, v22
	v_add_f32_e32 v23, 1.0, v23
	v_rcp_f32_e32 v16, v16
	v_rcp_f32_e32 v17, v17
	v_rcp_f32_e32 v18, v18
	v_rcp_f32_e32 v19, v19
	v_rcp_f32_e32 v20, v20
	v_rcp_f32_e32 v22, v22
	v_rcp_f32_e32 v23, v23
	v_rcp_f32_e32 v21, v21
	v_pk_mul_f32 v[18:19], v[14:15], v[18:19]
	v_pk_mul_f32 v[16:17], v[12:13], v[16:17]
	v_pk_mul_f32 v[22:23], v[10:11], v[22:23]
	v_pk_mul_f32 v[20:21], v[8:9], v[20:21]
	s_mov_b64 s[8:9], 0

; __device__ __forceinline__ u32x4 pack8(const float (&f)[8]) { u32x4 w; w.x = cvt_pk_bf16(f[0], f[1]); w.y = cvt_pk_bf16(f[2], f[3]); w.z = cvt_pk_bf16(f[4], f[5]); w.w = cvt_pk_bf16(f[6], f[7]); return w; }
; __device__ __forceinline__ float sigm(float x) { return __builtin_amdgcn_rcpf(1.f + __builtin_amdgcn_exp2f(-1.4426950408889634f * x)); }
;     __device__ __forceinline__ void operator()(const f32x4 (&acc)[2][2][4][2], const Unit& u, int wr, int wc, int fr, int fq) const {
;     ...
;         for (int ai = 0; ai < 2; ++ai)
; #pragma unroll
;             for (int m = 0; m < 4; ++m) { bf16_t* rowp = base + (size_t)(row0 + ai * HALF + m * 16) * ldc + col0;
; #pragma unroll
;                 for (int bj = 0; bj < 2; ++bj) { const f32x4 v0 = acc[ai][bj][m][0], v1 = acc[ai][bj][m][1];
;                     float f[8] = {v0[0], v0[1], v0[2], v0[3], v1[0], v1[1], v1[2], v1[3]};
;                     if (act == 1) {
; #pragma unroll
;                         for (int e = 0; e < 8; ++e) f[e] = sigm(f[e]);
;                     } else if (act == 2) {
; #pragma unroll
;                         for (int e = 0; e < 8; ++e) f[e] = f[e] * sigm(f[e]);
;                     }
;                     __builtin_nontemporal_store(pack8(f), (u32x4*)(rowp + bj * HALF)); } }
.LBB0_214:
	v_add_u32_e32 v8, 0xb0, v160
	v_ashrrev_i32_e32 v9, 31, v8
	v_mul_lo_u32 v10, s78, v9
	v_mul_lo_u32 v11, s79, v8
	v_mad_u64_u32 v[8:9], s[8:9], s78, v8, 0
	v_add3_u32 v9, v9, v10, v11
	v_lshl_add_u64 v[8:9], v[8:9], 1, v[120:121]
	v_cvt_pk_bf16_f32 v10, v16, v17
	v_cvt_pk_bf16_f32 v11, v18, v19
	v_cvt_pk_bf16_f32 v12, v20, v21
	v_cvt_pk_bf16_f32 v13, v22, v23
	s_and_b64 vcc, exec, s[6:7]
	s_mov_b64 s[6:7], -1
	ds_write_b128 v228, v[10:13]
	ds_read_b128 v[232:235], v229
	s_waitcnt lgkmcnt(0)
	global_store_dwordx4 v[8:9], v[232:235], off nt
	s_cbranch_vccnz .LBB0_217
	s_and_b64 vcc, exec, s[4:5]
	s_cbranch_vccnz .LBB0_237
	v_mul_f32_e32 v10, 0xbfb8aa3b, v4
	v_mul_f32_e32 v11, 0xbfb8aa3b, v5
	v_mul_f32_e32 v12, 0xbfb8aa3b, v6
	v_mul_f32_e32 v13, 0xbfb8aa3b, v7
	v_mul_f32_e32 v14, 0xbfb8aa3b, v0
	v_mul_f32_e32 v15, 0xbfb8aa3b, v1
	v_mul_f32_e32 v16, 0xbfb8aa3b, v2
	v_mul_f32_e32 v17, 0xbfb8aa3b, v3
	v_exp_f32_e32 v10, v10
	v_exp_f32_e32 v11, v11
	v_exp_f32_e32 v12, v12
	v_exp_f32_e32 v13, v13
	v_exp_f32_e32 v14, v14
	v_exp_f32_e32 v15, v15
	v_exp_f32_e32 v16, v16
	v_exp_f32_e32 v17, v17
	v_add_f32_e32 v10, 1.0, v10
	v_add_f32_e32 v11, 1.0, v11
	v_add_f32_e32 v12, 1.0, v12
	v_add_f32_e32 v13, 1.0, v13
	v_add_f32_e32 v14, 1.0, v14
	v_add_f32_e32 v15, 1.0, v15
	v_add_f32_e32 v16, 1.0, v16
	v_add_f32_e32 v17, 1.0, v17
	v_rcp_f32_e32 v10, v10
	v_rcp_f32_e32 v11, v11
	v_rcp_f32_e32 v12, v12
	v_rcp_f32_e32 v13, v13
	v_rcp_f32_e32 v14, v14
	v_rcp_f32_e32 v16, v16
	v_rcp_f32_e32 v17, v17
	v_rcp_f32_e32 v15, v15
	v_pk_mul_f32 v[12:13], v[6:7], v[12:13]
	v_pk_mul_f32 v[10:11], v[4:5], v[10:11]
	v_pk_mul_f32 v[16:17], v[2:3], v[16:17]
	v_pk_mul_f32 v[14:15], v[0:1], v[14:15]
	s_mov_b64 s[6:7], 0

; __device__ __forceinline__ u32x4 pack8(const float (&f)[8]) { u32x4 w; w.x = cvt_pk_bf16(f[0], f[1]); w.y = cvt_pk_bf16(f[2], f[3]); w.z = cvt_pk_bf16(f[4], f[5]); w.w = cvt_pk_bf16(f[6], f[7]); return w; }
; __device__ __forceinline__ float sigm(float x) { return __builtin_amdgcn_rcpf(1.f + __builtin_amdgcn_exp2f(-1.4426950408889634f * x)); }
;     __device__ __forceinline__ void operator()(const f32x4 (&acc)[2][2][4][2], const Unit& u, int wr, int wc, int fr, int fq) const {
;     ...
;         const int col0 = colt + wc * 32 + 8 * fq;
; #pragma unroll
;         for (int ai = 0; ai < 2; ++ai)
; #pragma unroll
;             for (int m = 0; m < 4; ++m) { bf16_t* rowp = base + (size_t)(row0 + ai * HALF + m * 16) * ldc + col0;
; #pragma unroll
;                 for (int bj = 0; bj < 2; ++bj) { const f32x4 v0 = acc[ai][bj][m][0], v1 = acc[ai][bj][m][1];
;                     float f[8] = {v0[0], v0[1], v0[2], v0[3], v1[0], v1[1], v1[2], v1[3]};
;                     if (act == 1) {
; #pragma unroll
;                         for (int e = 0; e < 8; ++e) f[e] = sigm(f[e]);
;                     } else if (act == 2) {
; #pragma unroll
;                         for (int e = 0; e < 8; ++e) f[e] = f[e] * sigm(f[e]);
;                     }
;                     __builtin_nontemporal_store(pack8(f), (u32x4*)(rowp + bj * HALF)); } }
.LBB0_219:
	s_andn2_b64 vcc, exec, s[0:1]
	s_mov_b64 s[0:1], -1
	v_cvt_pk_bf16_f32 v0, v10, v11
	v_cvt_pk_bf16_f32 v1, v12, v13
	v_cvt_pk_bf16_f32 v2, v14, v15
	v_cvt_pk_bf16_f32 v3, v16, v17
	ds_write_b128 v228, v[0:3]
	ds_read_b128 v[232:235], v229
	s_waitcnt lgkmcnt(0)
	global_store_dwordx4 v[8:9], v[232:235], off offset:256 nt
.Lp1_tail:
	s_cbranch_vccnz .LBB0_120
	s_andn2_b64 vcc, exec, s[16:17]
	s_cbranch_vccnz .LBB0_119
	s_barrier
	s_branch .LBB0_119
.Lp1_plain:
	v_lshl_add_u32 v160, s6, 8, v154
	v_add_u32_e32 v136, s3, v156
	s_add_u32 s98, s68, s80
	s_addc_u32 s99, s69, s81
	s_lshl_b32 s100, s78, 1
	v_mul_lo_u32 v160, v160, s100
	s_lshl_b32 s100, s78, 5
	s_mul_i32 s101, s78, 0xa0
	v_lshl_add_u32 v160, v136, 1, v160
	v_cvt_pk_bf16_f32 v124, v124, v125
	v_cvt_pk_bf16_f32 v125, v126, v127
	v_cvt_pk_bf16_f32 v126, v120, v121
	v_cvt_pk_bf16_f32 v127, v122, v123
	ds_write_b128 v228, v[124:127]
	ds_read_b128 v[120:123], v229
	v_cvt_pk_bf16_f32 v116, v116, v117
	v_cvt_pk_bf16_f32 v117, v118, v119
	v_cvt_pk_bf16_f32 v118, v112, v113
	v_cvt_pk_bf16_f32 v119, v114, v115
	ds_write_b128 v228, v[116:119]
	ds_read_b128 v[112:115], v229
	v_cvt_pk_bf16_f32 v108, v108, v109
	v_cvt_pk_bf16_f32 v109, v110, v111
	v_cvt_pk_bf16_f32 v110, v104, v105
	v_cvt_pk_bf16_f32 v111, v106, v107
	ds_write_b128 v228, v[108:111]
	ds_read_b128 v[104:107], v229
	v_cvt_pk_bf16_f32 v100, v100, v101
	v_cvt_pk_bf16_f32 v101, v102, v103
	v_cvt_pk_bf16_f32 v102, v96, v97
	v_cvt_pk_bf16_f32 v103, v98, v99
	ds_write_b128 v228, v[100:103]
	ds_read_b128 v[96:99], v229
	s_waitcnt lgkmcnt(6)
	global_store_dwordx4 v160, v[120:123], s[98:99] nt
	s_waitcnt lgkmcnt(4)
	global_store_dwordx4 v160, v[112:115], s[98:99] offset:256 nt
	v_add_u32_e32 v160, s100, v160
	s_waitcnt lgkmcnt(2)
	global_store_dwordx4 v160, v[104:107], s[98:99] nt
	s_waitcnt lgkmcnt(0)
	global_store_dwordx4 v160, v[96:99], s[98:99] offset:256 nt
	v_cvt_pk_bf16_f32 v92, v92, v93
	v_cvt_pk_bf16_f32 v93, v94, v95
	v_cvt_pk_bf16_f32 v94, v88, v89
	v_cvt_pk_bf16_f32 v95, v90, v91
	ds_write_b128 v228, v[92:95]
	ds_read_b128 v[88:91], v229
	v_cvt_pk_bf16_f32 v84, v84, v85
	v_cvt_pk_bf16_f32 v85, v86, v87
	v_cvt_pk_bf16_f32 v86, v80, v81
	v_cvt_pk_bf16_f32 v87, v82, v83
	ds_write_b128 v228, v[84:87]
	ds_read_b128 v[80:83], v229
	v_cvt_pk_bf16_f32 v76, v76, v77
	v_cvt_pk_bf16_f32 v77, v78, v79
	v_cvt_pk_bf16_f32 v78, v72, v73
	v_cvt_pk_bf16_f32 v79, v74, v75
	ds_write_b128 v228, v[76:79]
	ds_read_b128 v[72:75], v229
	v_cvt_pk_bf16_f32 v68, v68, v69
	v_cvt_pk_bf16_f32 v69, v70, v71
	v_cvt_pk_bf16_f32 v70, v64, v65
	v_cvt_pk_bf16_f32 v71, v66, v67
	ds_write_b128 v228, v[68:71]
	ds_read_b128 v[64:67], v229
	v_add_u32_e32 v160, s100, v160
	s_waitcnt lgkmcnt(6)
	global_store_dwordx4 v160, v[88:91], s[98:99] nt
	s_waitcnt lgkmcnt(4)
	global_store_dwordx4 v160, v[80:83], s[98:99] offset:256 nt
	v_add_u32_e32 v160, s100, v160
	s_waitcnt lgkmcnt(2)
	global_store_dwordx4 v160, v[72:75], s[98:99] nt
	s_waitcnt lgkmcnt(0)
	global_store_dwordx4 v160, v[64:67], s[98:99] offset:256 nt
	v_cvt_pk_bf16_f32 v60, v60, v61
	v_cvt_pk_bf16_f32 v61, v62, v63
	v_cvt_pk_bf16_f32 v62, v56, v57
	v_cvt_pk_bf16_f32 v63, v58, v59
	ds_write_b128 v228, v[60:63]
	ds_read_b128 v[56:59], v229
	v_cvt_pk_bf16_f32 v52, v52, v53
	v_cvt_pk_bf16_f32 v53, v54, v55
	v_cvt_pk_bf16_f32 v54, v48, v49
	v_cvt_pk_bf16_f32 v55, v50, v51
	ds_write_b128 v228, v[52:55]
	ds_read_b128 v[48:51], v229
	v_cvt_pk_bf16_f32 v44, v44, v45
	v_cvt_pk_bf16_f32 v45, v46, v47
	v_cvt_pk_bf16_f32 v46, v40, v41
	v_cvt_pk_bf16_f32 v47, v42, v43
	ds_write_b128 v228, v[44:47]
	ds_read_b128 v[40:43], v229
	v_cvt_pk_bf16_f32 v36, v36, v37
	v_cvt_pk_bf16_f32 v37, v38, v39
	v_cvt_pk_bf16_f32 v38, v32, v33
	v_cvt_pk_bf16_f32 v39, v34, v35
	ds_write_b128 v228, v[36:39]
	ds_read_b128 v[32:35], v229
	v_add_u32_e32 v160, s101, v160
	s_waitcnt lgkmcnt(6)
	global_store_dwordx4 v160, v[56:59], s[98:99] nt
	s_waitcnt lgkmcnt(4)
	global_store_dwordx4 v160, v[48:51], s[98:99] offset:256 nt
	v_add_u32_e32 v160, s100, v160
	s_waitcnt lgkmcnt(2)
	global_store_dwordx4 v160, v[40:43], s[98:99] nt
	s_waitcnt lgkmcnt(0)
	global_store_dwordx4 v160, v[32:35], s[98:99] offset:256 nt
	v_cvt_pk_bf16_f32 v28, v28, v29
	v_cvt_pk_bf16_f32 v29, v30, v31
	v_cvt_pk_bf16_f32 v30, v24, v25
	v_cvt_pk_bf16_f32 v31, v26, v27
	ds_write_b128 v228, v[28:31]
	ds_read_b128 v[24:27], v229
	v_cvt_pk_bf16_f32 v20, v20, v21
	v_cvt_pk_bf16_f32 v21, v22, v23
	v_cvt_pk_bf16_f32 v22, v16, v17
	v_cvt_pk_bf16_f32 v23, v18, v19
	ds_write_b128 v228, v[20:23]
	ds_read_b128 v[16:19], v229
	v_cvt_pk_bf16_f32 v12, v12, v13
	v_cvt_pk_bf16_f32 v13, v14, v15
	v_cvt_pk_bf16_f32 v14, v8, v9
	v_cvt_pk_bf16_f32 v15, v10, v11
	ds_write_b128 v228, v[12:15]
	ds_read_b128 v[8:11], v229
	v_cvt_pk_bf16_f32 v4, v4, v5
	v_cvt_pk_bf16_f32 v5, v6, v7
	v_cvt_pk_bf16_f32 v6, v0, v1
	v_cvt_pk_bf16_f32 v7, v2, v3
	ds_write_b128 v228, v[4:7]
	ds_read_b128 v[0:3], v229
	v_add_u32_e32 v160, s100, v160
	s_waitcnt lgkmcnt(6)
	global_store_dwordx4 v160, v[24:27], s[98:99] nt
	s_waitcnt lgkmcnt(4)
	global_store_dwordx4 v160, v[16:19], s[98:99] offset:256 nt
	v_add_u32_e32 v160, s100, v160
	s_waitcnt lgkmcnt(2)
	global_store_dwordx4 v160, v[8:11], s[98:99] nt
	s_waitcnt lgkmcnt(0)
	global_store_dwordx4 v160, v[0:3], s[98:99] offset:256 nt
	s_andn2_b64 vcc, exec, s[0:1]
	s_mov_b64 s[0:1], -1
	s_branch .Lp1_tail
